# SwiGLU epilogues (steps 0,5,7): row-scale table written by the leading half before its align barrier, the separate table barrier removed
# baseline (speedup 1.0000x reference)
.LBB0_459:
	s_add_u32 s14, s48, 0xfffc0080
	s_addc_u32 s15, s49, -1
	s_add_i32 s70, 0, 0x10000
	s_cmp_eq_u32 s51, 12
	s_cselect_b32 s15, s31, s15
	s_cselect_b32 s14, s43, s14
	v_add_u32_e32 v138, s70, v142
	s_cselect_b32 s61, s13, s17
	s_cselect_b32 s60, s50, s16
	s_add_i32 s84, 0, 0x14000
	ds_read_b128 v[134:137], v138
	ds_read_b128 v[148:151], v138 offset:1024
	ds_read_b128 v[152:155], v138 offset:2048
	ds_read_b128 v[156:159], v138 offset:3072
	v_add_u32_e32 v138, s84, v142
	ds_read_b128 v[160:163], v138
	ds_read_b128 v[164:167], v138 offset:1024
	ds_read_b128 v[168:171], v138 offset:2048
	ds_read_b128 v[172:175], v138 offset:3072
	v_lshl_add_u64 v[138:139], s[48:49], 0, v[132:133]
	s_add_i32 m0, s19, 0xc000
	ds_read_b128 v[176:179], v146
	ds_read_b128 v[180:183], v146 offset:1024
	ds_read_b128 v[194:197], v146 offset:2048
	ds_read_b128 v[198:201], v146 offset:3072
	ds_read_b128 v[202:205], v146 offset:4096
	ds_read_b128 v[206:209], v146 offset:5120
	ds_read_b128 v[210:213], v146 offset:6144
	ds_read_b128 v[214:217], v146 offset:7168
	global_load_lds_dwordx4 v[138:139], off
	v_lshl_add_u64 v[138:139], v[138:139], 0, s[34:35]
	s_add_i32 m0, s19, 0xe000
	s_nop 0
	global_load_lds_dwordx4 v[138:139], off
	s_waitcnt vmcnt(10)
	s_waitcnt lgkmcnt(0)
	s_barrier
	s_setprio 1
	s_waitcnt lgkmcnt(0)
	v_mfma_f32_16x16x32_bf16 v[124:127], v[134:137], v[176:179], v[124:127]
	v_mfma_f32_16x16x32_bf16 v[116:119], v[152:155], v[176:179], v[116:119]
	v_mfma_f32_16x16x32_bf16 v[108:111], v[134:137], v[194:197], v[108:111]
	v_mfma_f32_16x16x32_bf16 v[100:103], v[152:155], v[194:197], v[100:103]
	v_mfma_f32_16x16x32_bf16 v[92:95], v[134:137], v[202:205], v[92:95]
	v_mfma_f32_16x16x32_bf16 v[84:87], v[152:155], v[202:205], v[84:87]
	v_mfma_f32_16x16x32_bf16 v[76:79], v[134:137], v[210:213], v[76:79]
	v_mfma_f32_16x16x32_bf16 v[68:71], v[152:155], v[210:213], v[68:71]
	v_mfma_f32_16x16x32_bf16 v[124:127], v[148:151], v[180:183], v[124:127]
	v_mfma_f32_16x16x32_bf16 v[116:119], v[156:159], v[180:183], v[116:119]
	v_mfma_f32_16x16x32_bf16 v[108:111], v[148:151], v[198:201], v[108:111]
	v_mfma_f32_16x16x32_bf16 v[100:103], v[156:159], v[198:201], v[100:103]
	v_mfma_f32_16x16x32_bf16 v[92:95], v[148:151], v[206:209], v[92:95]
	v_mfma_f32_16x16x32_bf16 v[84:87], v[156:159], v[206:209], v[84:87]
	v_mfma_f32_16x16x32_bf16 v[76:79], v[148:151], v[214:217], v[76:79]
	v_mfma_f32_16x16x32_bf16 v[68:71], v[156:159], v[214:217], v[68:71]
	s_setprio 0
	s_setprio 1
	v_mfma_f32_16x16x32_bf16 v[120:123], v[160:163], v[176:179], v[120:123]
	v_mfma_f32_16x16x32_bf16 v[112:115], v[168:171], v[176:179], v[112:115]
	v_mfma_f32_16x16x32_bf16 v[104:107], v[160:163], v[194:197], v[104:107]
	v_mfma_f32_16x16x32_bf16 v[96:99], v[168:171], v[194:197], v[96:99]
	v_mfma_f32_16x16x32_bf16 v[88:91], v[160:163], v[202:205], v[88:91]
	v_mfma_f32_16x16x32_bf16 v[80:83], v[168:171], v[202:205], v[80:83]
	v_mfma_f32_16x16x32_bf16 v[72:75], v[160:163], v[210:213], v[72:75]
	v_mfma_f32_16x16x32_bf16 v[64:67], v[168:171], v[210:213], v[64:67]
	v_mfma_f32_16x16x32_bf16 v[120:123], v[164:167], v[180:183], v[120:123]
	v_mfma_f32_16x16x32_bf16 v[112:115], v[172:175], v[180:183], v[112:115]
	v_mfma_f32_16x16x32_bf16 v[104:107], v[164:167], v[198:201], v[104:107]
	v_mfma_f32_16x16x32_bf16 v[96:99], v[172:175], v[198:201], v[96:99]
	v_mfma_f32_16x16x32_bf16 v[88:91], v[164:167], v[206:209], v[88:91]
	v_mfma_f32_16x16x32_bf16 v[80:83], v[172:175], v[206:209], v[80:83]
	v_mfma_f32_16x16x32_bf16 v[72:75], v[164:167], v[214:217], v[72:75]
	v_mfma_f32_16x16x32_bf16 v[64:67], v[172:175], v[214:217], v[64:67]
	s_setprio 0
	s_barrier
	v_lshl_add_u64 v[138:139], s[60:61], 0, v[184:185]
	s_add_i32 s60, s70, s6
	s_mov_b32 m0, s60
	ds_read_b128 v[176:179], v146 offset:16384
	ds_read_b128 v[180:183], v146 offset:17408
	ds_read_b128 v[194:197], v146 offset:18432
	ds_read_b128 v[198:201], v146 offset:19456
	ds_read_b128 v[202:205], v146 offset:20480
	ds_read_b128 v[206:209], v146 offset:21504
	ds_read_b128 v[210:213], v146 offset:22528
	ds_read_b128 v[214:217], v146 offset:23552
	global_load_lds_dwordx4 v[138:139], off
	v_lshl_add_u64 v[218:219], v[138:139], 0, s[34:35]
	s_add_i32 m0, s60, 0x2000
	s_add_i32 s60, s84, s6
	global_load_lds_dwordx4 v[218:219], off
	v_lshl_add_u64 v[218:219], v[138:139], 0, s[92:93]
	s_mov_b32 m0, s60
	s_nop 0
	global_load_lds_dwordx4 v[218:219], off
	v_lshl_add_u64 v[218:219], v[138:139], 0, s[52:53]
	s_add_i32 m0, s60, 0x2000
	s_nop 0
	global_load_lds_dwordx4 v[218:219], off
	v_lshl_add_u64 v[218:219], s[14:15], 0, v[128:129]
	s_mov_b32 m0, s19
	v_lshl_add_u64 v[220:221], v[218:219], 0, s[34:35]
	global_load_lds_dwordx4 v[218:219], off
	s_mov_b32 m0, s20
	s_nop 0
	global_load_lds_dwordx4 v[220:221], off
	s_waitcnt vmcnt(14)
	s_waitcnt lgkmcnt(0)
	s_barrier
	s_setprio 1
	s_waitcnt lgkmcnt(0)
	v_mfma_f32_16x16x32_bf16 v[60:63], v[134:137], v[176:179], v[60:63]
	v_mfma_f32_16x16x32_bf16 v[52:55], v[152:155], v[176:179], v[52:55]
	v_mfma_f32_16x16x32_bf16 v[44:47], v[134:137], v[194:197], v[44:47]
	v_mfma_f32_16x16x32_bf16 v[36:39], v[152:155], v[194:197], v[36:39]
	v_mfma_f32_16x16x32_bf16 v[28:31], v[134:137], v[202:205], v[28:31]
	v_mfma_f32_16x16x32_bf16 v[20:23], v[152:155], v[202:205], v[20:23]
	v_mfma_f32_16x16x32_bf16 v[12:15], v[134:137], v[210:213], v[12:15]
	v_mfma_f32_16x16x32_bf16 v[4:7], v[152:155], v[210:213], v[4:7]
	v_mfma_f32_16x16x32_bf16 v[60:63], v[148:151], v[180:183], v[60:63]
	v_mfma_f32_16x16x32_bf16 v[52:55], v[156:159], v[180:183], v[52:55]
	v_mfma_f32_16x16x32_bf16 v[44:47], v[148:151], v[198:201], v[44:47]
	v_mfma_f32_16x16x32_bf16 v[36:39], v[156:159], v[198:201], v[36:39]
	v_mfma_f32_16x16x32_bf16 v[28:31], v[148:151], v[206:209], v[28:31]
	v_mfma_f32_16x16x32_bf16 v[20:23], v[156:159], v[206:209], v[20:23]
	v_mfma_f32_16x16x32_bf16 v[12:15], v[148:151], v[214:217], v[12:15]
	v_mfma_f32_16x16x32_bf16 v[4:7], v[156:159], v[214:217], v[4:7]
	s_setprio 0
	s_setprio 1
	v_mfma_f32_16x16x32_bf16 v[56:59], v[160:163], v[176:179], v[56:59]
	v_mfma_f32_16x16x32_bf16 v[48:51], v[168:171], v[176:179], v[48:51]
	v_mfma_f32_16x16x32_bf16 v[40:43], v[160:163], v[194:197], v[40:43]
	v_mfma_f32_16x16x32_bf16 v[32:35], v[168:171], v[194:197], v[32:35]
	v_mfma_f32_16x16x32_bf16 v[24:27], v[160:163], v[202:205], v[24:27]
	v_mfma_f32_16x16x32_bf16 v[16:19], v[168:171], v[202:205], v[16:19]
	v_mfma_f32_16x16x32_bf16 v[8:11], v[160:163], v[210:213], v[8:11]
	v_mfma_f32_16x16x32_bf16 v[0:3], v[168:171], v[210:213], v[0:3]
	v_mfma_f32_16x16x32_bf16 v[56:59], v[164:167], v[180:183], v[56:59]
	v_mfma_f32_16x16x32_bf16 v[48:51], v[172:175], v[180:183], v[48:51]
	v_mfma_f32_16x16x32_bf16 v[40:43], v[164:167], v[198:201], v[40:43]
	v_mfma_f32_16x16x32_bf16 v[32:35], v[172:175], v[198:201], v[32:35]
	v_mfma_f32_16x16x32_bf16 v[24:27], v[164:167], v[206:209], v[24:27]
	v_mfma_f32_16x16x32_bf16 v[16:19], v[172:175], v[206:209], v[16:19]
	v_mfma_f32_16x16x32_bf16 v[8:11], v[164:167], v[214:217], v[8:11]
	v_mfma_f32_16x16x32_bf16 v[0:3], v[172:175], v[214:217], v[0:3]
	s_setprio 0
	s_barrier
	s_add_i32 s14, 0, 0x18000
	v_add_u32_e32 v147, s14, v142
	s_add_i32 s15, 0, 0x1c000
	ds_read_b128 v[134:137], v147
	ds_read_b128 v[148:151], v147 offset:1024
	ds_read_b128 v[152:155], v147 offset:2048
	ds_read_b128 v[156:159], v147 offset:3072
	v_add_u32_e32 v147, s15, v142
	ds_read_b128 v[160:163], v147
	ds_read_b128 v[164:167], v147 offset:1024
	ds_read_b128 v[168:171], v147 offset:2048
	ds_read_b128 v[172:175], v147 offset:3072
	s_mov_b32 m0, s24
	v_lshl_add_u64 v[220:221], v[218:219], 0, s[92:93]
	ds_read_b128 v[176:179], v146 offset:32768
	ds_read_b128 v[180:183], v146 offset:33792
	ds_read_b128 v[194:197], v146 offset:34816
	ds_read_b128 v[198:201], v146 offset:35840
	ds_read_b128 v[202:205], v146 offset:36864
	ds_read_b128 v[206:209], v146 offset:37888
	ds_read_b128 v[210:213], v146 offset:38912
	ds_read_b128 v[214:217], v146 offset:39936
	global_load_lds_dwordx4 v[220:221], off
	v_lshl_add_u64 v[220:221], v[218:219], 0, s[52:53]
	s_mov_b32 m0, s25
	s_nop 0
	global_load_lds_dwordx4 v[220:221], off
	s_waitcnt vmcnt(10)
	s_waitcnt lgkmcnt(0)
	s_barrier
	s_setprio 1
	s_waitcnt lgkmcnt(0)
	v_mfma_f32_16x16x32_bf16 v[124:127], v[134:137], v[176:179], v[124:127]
	v_mfma_f32_16x16x32_bf16 v[116:119], v[152:155], v[176:179], v[116:119]
	v_mfma_f32_16x16x32_bf16 v[108:111], v[134:137], v[194:197], v[108:111]
	v_mfma_f32_16x16x32_bf16 v[100:103], v[152:155], v[194:197], v[100:103]
	v_mfma_f32_16x16x32_bf16 v[92:95], v[134:137], v[202:205], v[92:95]
	v_mfma_f32_16x16x32_bf16 v[84:87], v[152:155], v[202:205], v[84:87]
	v_mfma_f32_16x16x32_bf16 v[76:79], v[134:137], v[210:213], v[76:79]
	v_mfma_f32_16x16x32_bf16 v[68:71], v[152:155], v[210:213], v[68:71]
	v_mfma_f32_16x16x32_bf16 v[124:127], v[148:151], v[180:183], v[124:127]
	v_mfma_f32_16x16x32_bf16 v[116:119], v[156:159], v[180:183], v[116:119]
	v_mfma_f32_16x16x32_bf16 v[108:111], v[148:151], v[198:201], v[108:111]
	v_mfma_f32_16x16x32_bf16 v[100:103], v[156:159], v[198:201], v[100:103]
	v_mfma_f32_16x16x32_bf16 v[92:95], v[148:151], v[206:209], v[92:95]
	v_mfma_f32_16x16x32_bf16 v[84:87], v[156:159], v[206:209], v[84:87]
	v_mfma_f32_16x16x32_bf16 v[76:79], v[148:151], v[214:217], v[76:79]
	v_mfma_f32_16x16x32_bf16 v[68:71], v[156:159], v[214:217], v[68:71]
	s_setprio 0
	s_setprio 1
	v_mfma_f32_16x16x32_bf16 v[120:123], v[160:163], v[176:179], v[120:123]
	v_mfma_f32_16x16x32_bf16 v[112:115], v[168:171], v[176:179], v[112:115]
	v_mfma_f32_16x16x32_bf16 v[104:107], v[160:163], v[194:197], v[104:107]
	v_mfma_f32_16x16x32_bf16 v[96:99], v[168:171], v[194:197], v[96:99]
	v_mfma_f32_16x16x32_bf16 v[88:91], v[160:163], v[202:205], v[88:91]
	v_mfma_f32_16x16x32_bf16 v[80:83], v[168:171], v[202:205], v[80:83]
	v_mfma_f32_16x16x32_bf16 v[72:75], v[160:163], v[210:213], v[72:75]
	v_mfma_f32_16x16x32_bf16 v[64:67], v[168:171], v[210:213], v[64:67]
	v_mfma_f32_16x16x32_bf16 v[120:123], v[164:167], v[180:183], v[120:123]
	v_mfma_f32_16x16x32_bf16 v[112:115], v[172:175], v[180:183], v[112:115]
	v_mfma_f32_16x16x32_bf16 v[104:107], v[164:167], v[198:201], v[104:107]
	v_mfma_f32_16x16x32_bf16 v[96:99], v[172:175], v[198:201], v[96:99]
	v_mfma_f32_16x16x32_bf16 v[88:91], v[164:167], v[206:209], v[88:91]
	v_mfma_f32_16x16x32_bf16 v[80:83], v[172:175], v[206:209], v[80:83]
	v_mfma_f32_16x16x32_bf16 v[72:75], v[164:167], v[214:217], v[72:75]
	v_mfma_f32_16x16x32_bf16 v[64:67], v[172:175], v[214:217], v[64:67]
	s_setprio 0
	s_barrier
	s_add_i32 s14, s14, s6
	v_lshl_add_u64 v[220:221], v[138:139], 0, s[56:57]
	s_mov_b32 m0, s14
	ds_read_b128 v[176:179], v146 offset:49152
	ds_read_b128 v[180:183], v146 offset:50176
	ds_read_b128 v[194:197], v146 offset:51200
	ds_read_b128 v[198:201], v146 offset:52224
	ds_read_b128 v[202:205], v146 offset:53248
	ds_read_b128 v[206:209], v146 offset:54272
	ds_read_b128 v[210:213], v146 offset:55296
	ds_read_b128 v[214:217], v146 offset:56320
	global_load_lds_dwordx4 v[220:221], off
	v_lshl_add_u64 v[220:221], v[138:139], 0, s[96:97]
	s_add_i32 m0, s14, 0x2000
	s_add_i32 s14, s15, s6
	global_load_lds_dwordx4 v[220:221], off
	v_lshl_add_u64 v[220:221], v[138:139], 0, s[88:89]
	s_mov_b32 m0, s14
	v_lshl_add_u64 v[138:139], v[138:139], 0, s[68:69]
	global_load_lds_dwordx4 v[220:221], off
	s_add_i32 m0, s14, 0x2000
	s_nop 0
	global_load_lds_dwordx4 v[138:139], off
	v_lshl_add_u64 v[138:139], v[218:219], 0, s[56:57]
	s_mov_b32 m0, s26
	s_nop 0
	global_load_lds_dwordx4 v[138:139], off
	v_lshl_add_u64 v[138:139], v[218:219], 0, s[96:97]
	s_mov_b32 m0, s27
	s_nop 0
	global_load_lds_dwordx4 v[138:139], off
	s_waitcnt vmcnt(14)
	s_waitcnt lgkmcnt(0)
	s_barrier
	s_setprio 1
	s_waitcnt lgkmcnt(0)
	v_mfma_f32_16x16x32_bf16 v[60:63], v[134:137], v[176:179], v[60:63]
	v_mfma_f32_16x16x32_bf16 v[52:55], v[152:155], v[176:179], v[52:55]
	v_mfma_f32_16x16x32_bf16 v[44:47], v[134:137], v[194:197], v[44:47]
	v_mfma_f32_16x16x32_bf16 v[36:39], v[152:155], v[194:197], v[36:39]
	v_mfma_f32_16x16x32_bf16 v[28:31], v[134:137], v[202:205], v[28:31]
	v_mfma_f32_16x16x32_bf16 v[20:23], v[152:155], v[202:205], v[20:23]
	v_mfma_f32_16x16x32_bf16 v[12:15], v[134:137], v[210:213], v[12:15]
	v_mfma_f32_16x16x32_bf16 v[4:7], v[152:155], v[210:213], v[4:7]
	v_mfma_f32_16x16x32_bf16 v[60:63], v[148:151], v[180:183], v[60:63]
	v_mfma_f32_16x16x32_bf16 v[52:55], v[156:159], v[180:183], v[52:55]
	v_mfma_f32_16x16x32_bf16 v[44:47], v[148:151], v[198:201], v[44:47]
	v_mfma_f32_16x16x32_bf16 v[36:39], v[156:159], v[198:201], v[36:39]
	v_mfma_f32_16x16x32_bf16 v[28:31], v[148:151], v[206:209], v[28:31]
	v_mfma_f32_16x16x32_bf16 v[20:23], v[156:159], v[206:209], v[20:23]
	v_mfma_f32_16x16x32_bf16 v[12:15], v[148:151], v[214:217], v[12:15]
	v_mfma_f32_16x16x32_bf16 v[4:7], v[156:159], v[214:217], v[4:7]
	s_setprio 0
	s_setprio 1
	v_mfma_f32_16x16x32_bf16 v[56:59], v[160:163], v[176:179], v[56:59]
	v_mfma_f32_16x16x32_bf16 v[48:51], v[168:171], v[176:179], v[48:51]
	v_mfma_f32_16x16x32_bf16 v[40:43], v[160:163], v[194:197], v[40:43]
	v_mfma_f32_16x16x32_bf16 v[32:35], v[168:171], v[194:197], v[32:35]
	v_mfma_f32_16x16x32_bf16 v[24:27], v[160:163], v[202:205], v[24:27]
	v_mfma_f32_16x16x32_bf16 v[16:19], v[168:171], v[202:205], v[16:19]
	v_mfma_f32_16x16x32_bf16 v[8:11], v[160:163], v[210:213], v[8:11]
	v_mfma_f32_16x16x32_bf16 v[0:3], v[168:171], v[210:213], v[0:3]
	v_mfma_f32_16x16x32_bf16 v[56:59], v[164:167], v[180:183], v[56:59]
	v_mfma_f32_16x16x32_bf16 v[48:51], v[172:175], v[180:183], v[48:51]
	v_mfma_f32_16x16x32_bf16 v[40:43], v[164:167], v[198:201], v[40:43]
	v_mfma_f32_16x16x32_bf16 v[32:35], v[172:175], v[198:201], v[32:35]
	v_mfma_f32_16x16x32_bf16 v[24:27], v[164:167], v[206:209], v[24:27]
	v_mfma_f32_16x16x32_bf16 v[16:19], v[172:175], v[206:209], v[16:19]
	v_mfma_f32_16x16x32_bf16 v[8:11], v[164:167], v[214:217], v[8:11]
	v_mfma_f32_16x16x32_bf16 v[0:3], v[172:175], v[214:217], v[0:3]
	s_setprio 0
	s_barrier
	s_add_i32 s51, s51, 2
	s_add_u32 s48, s48, 0x100
	s_addc_u32 s49, s49, 0
	s_add_u32 s16, s16, 0x100
	s_addc_u32 s17, s17, 0
	s_cmp_gt_u32 s51, 13
	s_cbranch_scc0 .LBB0_459
	s_and_b64 vcc, exec, s[10:11]
	s_cbranch_vccz .LBB0_462
	v_cvt_f32_u32_e32 v134, v140
	v_fmamk_f32 v134, v134, 0x35800000, v242
	v_rsq_f32_e32 v134, v134
	s_nop 0
	v_cndmask_b32_e64 v134, v134, 1.0, s[78:79]
	ds_write_b32 v143, v134
	s_waitcnt lgkmcnt(0)
	s_barrier

.Lnochk462:
	s_mov_b32 s84, 0x2aaaaaab
	s_mov_b64 s[48:49], 0x84000
	ds_read2_b32 v[148:149], v144 offset1:16
	v_pk_mul_f32 v[120:121], v[124:125], v[120:121]
	v_pk_mul_f32 v[122:123], v[126:127], v[122:123]
	ds_read2_b32 v[138:139], v144 offset0:32 offset1:48
	ds_read2_b32 v[136:137], v144 offset0:128 offset1:144
	ds_read2_b32 v[134:135], v144 offset0:160 offset1:176
	v_pk_mul_f32 v[112:113], v[116:117], v[112:113]
	s_waitcnt lgkmcnt(0)
	v_mul_f32_e32 v150, 0xbfb8aa3b, v148
	v_pk_mul_f32 v[152:153], v[124:125], v[150:151] op_sel_hi:[1,0]
	v_pk_mul_f32 v[124:125], v[126:127], v[150:151] op_sel_hi:[1,0]
	v_exp_f32_e32 v152, v152
	v_exp_f32_e32 v124, v124
	v_exp_f32_e32 v125, v125
	v_exp_f32_e32 v153, v153
	v_mul_f32_e32 v148, v148, v148
	v_pk_mul_f32 v[126:127], v[116:117], v[150:151] op_sel_hi:[1,0]
	v_pk_add_f32 v[124:125], v[124:125], 1.0 op_sel_hi:[1,0]
	v_pk_add_f32 v[152:153], v[152:153], 1.0 op_sel_hi:[1,0]
	v_rcp_f32_e32 v124, v124
	v_rcp_f32_e32 v125, v125
	v_rcp_f32_e32 v152, v152
	v_rcp_f32_e32 v153, v153
	v_exp_f32_e32 v126, v126
	v_exp_f32_e32 v127, v127
	v_pk_mul_f32 v[122:123], v[122:123], v[148:149] op_sel_hi:[1,0]
	v_pk_mul_f32 v[120:121], v[120:121], v[148:149] op_sel_hi:[1,0]
	v_pk_mul_f32 v[122:123], v[122:123], v[124:125]
	v_pk_mul_f32 v[124:125], v[118:119], v[150:151] op_sel_hi:[1,0]
	v_pk_mul_f32 v[120:121], v[120:121], v[152:153]
	v_exp_f32_e32 v124, v124
	v_exp_f32_e32 v125, v125
	v_cvt_pk_bf16_f32 v120, v120, v121
	v_cvt_pk_bf16_f32 v121, v122, v123
	v_pk_add_f32 v[122:123], v[126:127], 1.0 op_sel_hi:[1,0]
	v_pk_add_f32 v[116:117], v[124:125], 1.0 op_sel_hi:[1,0]
	v_rcp_f32_e32 v122, v122
	v_rcp_f32_e32 v123, v123
	v_pk_mul_f32 v[114:115], v[118:119], v[114:115]
	v_rcp_f32_e32 v116, v116
	v_rcp_f32_e32 v117, v117
	v_mul_f32_e32 v118, 0xbfb8aa3b, v149
	v_pk_mul_f32 v[112:113], v[112:113], v[148:149] op_sel_hi:[1,0]
	v_pk_mul_f32 v[124:125], v[108:109], v[118:119] op_sel_hi:[1,0]
	v_pk_mul_f32 v[104:105], v[108:109], v[104:105]
	v_pk_mul_f32 v[108:109], v[110:111], v[118:119] op_sel_hi:[1,0]
	v_pk_mul_f32 v[112:113], v[112:113], v[122:123]
	v_exp_f32_e32 v108, v108
	v_exp_f32_e32 v109, v109
	v_cvt_pk_bf16_f32 v122, v112, v113
	v_pk_mul_f32 v[112:113], v[114:115], v[148:149] op_sel_hi:[1,0]
	v_lshl_or_b32 v154, s29, 7, v145
	v_pk_mul_f32 v[112:113], v[112:113], v[116:117]
	v_exp_f32_e32 v124, v124
	v_exp_f32_e32 v125, v125
	v_lshl_add_u32 v147, s30, 8, v141
	v_ashrrev_i32_e32 v155, 31, v154
	v_cvt_pk_bf16_f32 v123, v112, v113
	v_mov_b64_e32 v[112:113], s[72:73]
	v_mad_i64_i32 v[116:117], s[14:15], v147, s18, v[112:113]
	v_lshlrev_b64 v[114:115], 1, v[154:155]
	v_pk_add_f32 v[108:109], v[108:109], 1.0 op_sel_hi:[1,0]
	v_lshl_add_u64 v[116:117], v[116:117], 0, v[114:115]
	v_rcp_f32_e32 v108, v108
	v_rcp_f32_e32 v109, v109
	global_store_dwordx4 v[116:117], v[120:123], off
	v_mul_f32_e32 v116, v149, v149
	v_pk_mul_f32 v[106:107], v[110:111], v[106:107]
	v_pk_add_f32 v[120:121], v[124:125], 1.0 op_sel_hi:[1,0]
	v_pk_mul_f32 v[110:111], v[100:101], v[118:119] op_sel_hi:[1,0]
	v_rcp_f32_e32 v120, v120
	v_rcp_f32_e32 v121, v121
	v_exp_f32_e32 v110, v110
	v_exp_f32_e32 v111, v111
	v_pk_mul_f32 v[106:107], v[106:107], v[116:117] op_sel_hi:[1,0]
	v_pk_mul_f32 v[104:105], v[104:105], v[116:117] op_sel_hi:[1,0]
	v_pk_mul_f32 v[106:107], v[106:107], v[108:109]
	v_pk_mul_f32 v[108:109], v[102:103], v[118:119] op_sel_hi:[1,0]
	v_pk_mul_f32 v[104:105], v[104:105], v[120:121]
	v_exp_f32_e32 v108, v108
	v_exp_f32_e32 v109, v109
	v_cvt_pk_bf16_f32 v104, v104, v105
	v_cvt_pk_bf16_f32 v105, v106, v107
	v_pk_add_f32 v[106:107], v[110:111], 1.0 op_sel_hi:[1,0]
	v_pk_mul_f32 v[96:97], v[100:101], v[96:97]
	v_rcp_f32_e32 v106, v106
	v_rcp_f32_e32 v107, v107
	v_pk_add_f32 v[100:101], v[108:109], 1.0 op_sel_hi:[1,0]
	v_pk_mul_f32 v[96:97], v[96:97], v[116:117] op_sel_hi:[1,0]
	v_rcp_f32_e32 v100, v100
	v_rcp_f32_e32 v101, v101
	v_pk_mul_f32 v[98:99], v[102:103], v[98:99]
	v_pk_mul_f32 v[96:97], v[96:97], v[106:107]
	v_pk_mul_f32 v[88:89], v[92:93], v[88:89]
	v_cvt_pk_bf16_f32 v106, v96, v97
	v_pk_mul_f32 v[96:97], v[98:99], v[116:117] op_sel_hi:[1,0]
	v_mul_f32_e32 v98, 0xbfb8aa3b, v138
	v_pk_mul_f32 v[96:97], v[96:97], v[100:101]
	v_pk_mul_f32 v[100:101], v[92:93], v[98:99] op_sel_hi:[1,0]
	v_pk_mul_f32 v[92:93], v[94:95], v[98:99] op_sel_hi:[1,0]
	v_exp_f32_e32 v100, v100
	v_exp_f32_e32 v92, v92
	v_exp_f32_e32 v93, v93
	v_exp_f32_e32 v101, v101
	v_cvt_pk_bf16_f32 v107, v96, v97
	v_or_b32_e32 v96, 16, v147
	v_pk_add_f32 v[92:93], v[92:93], 1.0 op_sel_hi:[1,0]
	v_mad_i64_i32 v[96:97], s[14:15], v96, s18, v[112:113]
	v_rcp_f32_e32 v92, v92
	v_rcp_f32_e32 v93, v93
	v_lshl_add_u64 v[96:97], v[96:97], 0, v[114:115]
	v_pk_add_f32 v[100:101], v[100:101], 1.0 op_sel_hi:[1,0]
	global_store_dwordx4 v[96:97], v[104:107], off
	v_mul_f32_e32 v96, v138, v138
	v_rcp_f32_e32 v100, v100
	v_rcp_f32_e32 v101, v101
	v_pk_mul_f32 v[90:91], v[94:95], v[90:91]
	v_pk_mul_f32 v[94:95], v[84:85], v[98:99] op_sel_hi:[1,0]
	v_pk_mul_f32 v[90:91], v[90:91], v[96:97] op_sel_hi:[1,0]
	v_exp_f32_e32 v94, v94
	v_exp_f32_e32 v95, v95
	v_pk_mul_f32 v[90:91], v[90:91], v[92:93]
	v_pk_mul_f32 v[92:93], v[86:87], v[98:99] op_sel_hi:[1,0]
	v_pk_mul_f32 v[88:89], v[88:89], v[96:97] op_sel_hi:[1,0]
	v_exp_f32_e32 v92, v92
	v_exp_f32_e32 v93, v93
	v_pk_mul_f32 v[88:89], v[88:89], v[100:101]
	v_pk_mul_f32 v[80:81], v[84:85], v[80:81]
	v_cvt_pk_bf16_f32 v88, v88, v89
	v_cvt_pk_bf16_f32 v89, v90, v91
	v_pk_add_f32 v[90:91], v[94:95], 1.0 op_sel_hi:[1,0]
	v_pk_add_f32 v[84:85], v[92:93], 1.0 op_sel_hi:[1,0]
	v_rcp_f32_e32 v90, v90
	v_rcp_f32_e32 v91, v91
	v_rcp_f32_e32 v84, v84
	v_rcp_f32_e32 v85, v85
	v_pk_mul_f32 v[80:81], v[80:81], v[96:97] op_sel_hi:[1,0]
	v_pk_mul_f32 v[82:83], v[86:87], v[82:83]
	v_pk_mul_f32 v[80:81], v[80:81], v[90:91]
	v_pk_mul_f32 v[72:73], v[76:77], v[72:73]
	v_cvt_pk_bf16_f32 v90, v80, v81
	v_pk_mul_f32 v[80:81], v[82:83], v[96:97] op_sel_hi:[1,0]
	v_mul_f32_e32 v82, 0xbfb8aa3b, v139
	v_pk_mul_f32 v[80:81], v[80:81], v[84:85]
	v_pk_mul_f32 v[84:85], v[76:77], v[82:83] op_sel_hi:[1,0]
	v_pk_mul_f32 v[76:77], v[78:79], v[82:83] op_sel_hi:[1,0]
	v_exp_f32_e32 v84, v84
	v_exp_f32_e32 v76, v76
	v_exp_f32_e32 v77, v77
	v_exp_f32_e32 v85, v85
	v_cvt_pk_bf16_f32 v91, v80, v81
	v_or_b32_e32 v80, 32, v147
	v_pk_add_f32 v[76:77], v[76:77], 1.0 op_sel_hi:[1,0]
	v_mad_i64_i32 v[80:81], s[14:15], v80, s18, v[112:113]
	v_rcp_f32_e32 v76, v76
	v_rcp_f32_e32 v77, v77
	v_lshl_add_u64 v[80:81], v[80:81], 0, v[114:115]
	v_pk_add_f32 v[84:85], v[84:85], 1.0 op_sel_hi:[1,0]
	global_store_dwordx4 v[80:81], v[88:91], off
	v_mul_f32_e32 v80, v139, v139
	v_rcp_f32_e32 v84, v84
	v_rcp_f32_e32 v85, v85
	v_pk_mul_f32 v[74:75], v[78:79], v[74:75]
	v_pk_mul_f32 v[78:79], v[68:69], v[82:83] op_sel_hi:[1,0]
	v_pk_mul_f32 v[74:75], v[74:75], v[80:81] op_sel_hi:[1,0]
	v_exp_f32_e32 v78, v78
	v_exp_f32_e32 v79, v79
	v_pk_mul_f32 v[74:75], v[74:75], v[76:77]
	v_pk_mul_f32 v[76:77], v[70:71], v[82:83] op_sel_hi:[1,0]
	v_pk_mul_f32 v[72:73], v[72:73], v[80:81] op_sel_hi:[1,0]
	v_exp_f32_e32 v76, v76
	v_exp_f32_e32 v77, v77
	v_pk_mul_f32 v[72:73], v[72:73], v[84:85]
	v_pk_mul_f32 v[64:65], v[68:69], v[64:65]
	v_cvt_pk_bf16_f32 v72, v72, v73
	v_cvt_pk_bf16_f32 v73, v74, v75
	v_pk_add_f32 v[74:75], v[78:79], 1.0 op_sel_hi:[1,0]
	v_pk_add_f32 v[68:69], v[76:77], 1.0 op_sel_hi:[1,0]
	v_rcp_f32_e32 v74, v74
	v_rcp_f32_e32 v75, v75
	v_rcp_f32_e32 v68, v68
	v_rcp_f32_e32 v69, v69
	v_pk_mul_f32 v[64:65], v[64:65], v[80:81] op_sel_hi:[1,0]
	v_pk_mul_f32 v[66:67], v[70:71], v[66:67]
	v_pk_mul_f32 v[64:65], v[64:65], v[74:75]
	v_pk_mul_f32 v[56:57], v[60:61], v[56:57]
	v_cvt_pk_bf16_f32 v74, v64, v65
	v_pk_mul_f32 v[64:65], v[66:67], v[80:81] op_sel_hi:[1,0]
	v_mul_f32_e32 v66, 0xbfb8aa3b, v136
	v_pk_mul_f32 v[64:65], v[64:65], v[68:69]
	v_pk_mul_f32 v[68:69], v[60:61], v[66:67] op_sel_hi:[1,0]
	v_pk_mul_f32 v[60:61], v[62:63], v[66:67] op_sel_hi:[1,0]
	v_exp_f32_e32 v68, v68
	v_exp_f32_e32 v60, v60
	v_exp_f32_e32 v61, v61
	v_exp_f32_e32 v69, v69
	v_cvt_pk_bf16_f32 v75, v64, v65
	v_or_b32_e32 v64, 48, v147
	v_pk_add_f32 v[60:61], v[60:61], 1.0 op_sel_hi:[1,0]
	v_mad_i64_i32 v[64:65], s[14:15], v64, s18, v[112:113]
	v_rcp_f32_e32 v60, v60
	v_rcp_f32_e32 v61, v61
	v_lshl_add_u64 v[64:65], v[64:65], 0, v[114:115]
	v_pk_add_f32 v[68:69], v[68:69], 1.0 op_sel_hi:[1,0]
	global_store_dwordx4 v[64:65], v[72:75], off
	v_add_u32_e32 v65, 0x80, v147
	v_mul_f32_e32 v64, v136, v136
	v_rcp_f32_e32 v68, v68
	v_rcp_f32_e32 v69, v69
	v_pk_mul_f32 v[58:59], v[62:63], v[58:59]
	v_pk_mul_f32 v[62:63], v[52:53], v[66:67] op_sel_hi:[1,0]
	v_pk_mul_f32 v[58:59], v[58:59], v[64:65] op_sel_hi:[1,0]
	v_exp_f32_e32 v62, v62
	v_exp_f32_e32 v63, v63
	v_pk_mul_f32 v[58:59], v[58:59], v[60:61]
	v_pk_mul_f32 v[60:61], v[54:55], v[66:67] op_sel_hi:[1,0]
	v_pk_mul_f32 v[56:57], v[56:57], v[64:65] op_sel_hi:[1,0]
	v_exp_f32_e32 v60, v60
	v_exp_f32_e32 v61, v61
	v_pk_mul_f32 v[56:57], v[56:57], v[68:69]
	v_pk_mul_f32 v[48:49], v[52:53], v[48:49]
	v_cvt_pk_bf16_f32 v56, v56, v57
	v_cvt_pk_bf16_f32 v57, v58, v59
	v_pk_add_f32 v[58:59], v[62:63], 1.0 op_sel_hi:[1,0]
	v_pk_add_f32 v[52:53], v[60:61], 1.0 op_sel_hi:[1,0]
	v_rcp_f32_e32 v58, v58
	v_rcp_f32_e32 v59, v59
	v_rcp_f32_e32 v52, v52
	v_rcp_f32_e32 v53, v53
	v_pk_mul_f32 v[48:49], v[48:49], v[64:65] op_sel_hi:[1,0]
	v_pk_mul_f32 v[50:51], v[54:55], v[50:51]
	v_pk_mul_f32 v[48:49], v[48:49], v[58:59]
	v_pk_mul_f32 v[40:41], v[44:45], v[40:41]
	v_cvt_pk_bf16_f32 v58, v48, v49
	v_pk_mul_f32 v[48:49], v[50:51], v[64:65] op_sel_hi:[1,0]
	v_mul_f32_e32 v50, 0xbfb8aa3b, v137
	v_pk_mul_f32 v[48:49], v[48:49], v[52:53]
	v_pk_mul_f32 v[52:53], v[44:45], v[50:51] op_sel_hi:[1,0]
	v_pk_mul_f32 v[44:45], v[46:47], v[50:51] op_sel_hi:[1,0]
	v_exp_f32_e32 v52, v52
	v_exp_f32_e32 v44, v44
	v_exp_f32_e32 v45, v45
	v_exp_f32_e32 v53, v53
	v_cvt_pk_bf16_f32 v59, v48, v49
	v_mad_i64_i32 v[48:49], s[14:15], v65, s18, v[112:113]
	v_pk_add_f32 v[44:45], v[44:45], 1.0 op_sel_hi:[1,0]
	v_lshl_add_u64 v[48:49], v[48:49], 0, v[114:115]
	v_rcp_f32_e32 v44, v44
	v_rcp_f32_e32 v45, v45
	v_pk_add_f32 v[52:53], v[52:53], 1.0 op_sel_hi:[1,0]
	global_store_dwordx4 v[48:49], v[56:59], off
	v_mul_f32_e32 v48, v137, v137
	v_rcp_f32_e32 v52, v52
	v_rcp_f32_e32 v53, v53
	v_pk_mul_f32 v[42:43], v[46:47], v[42:43]
	v_pk_mul_f32 v[46:47], v[36:37], v[50:51] op_sel_hi:[1,0]
	v_pk_mul_f32 v[42:43], v[42:43], v[48:49] op_sel_hi:[1,0]
	v_exp_f32_e32 v46, v46
	v_exp_f32_e32 v47, v47
	v_pk_mul_f32 v[42:43], v[42:43], v[44:45]
	v_pk_mul_f32 v[44:45], v[38:39], v[50:51] op_sel_hi:[1,0]
	v_pk_mul_f32 v[40:41], v[40:41], v[48:49] op_sel_hi:[1,0]
	v_exp_f32_e32 v44, v44
	v_exp_f32_e32 v45, v45
	v_pk_mul_f32 v[40:41], v[40:41], v[52:53]
	v_pk_mul_f32 v[32:33], v[36:37], v[32:33]
	v_cvt_pk_bf16_f32 v40, v40, v41
	v_cvt_pk_bf16_f32 v41, v42, v43
	v_pk_add_f32 v[42:43], v[46:47], 1.0 op_sel_hi:[1,0]
	v_pk_add_f32 v[36:37], v[44:45], 1.0 op_sel_hi:[1,0]
	v_rcp_f32_e32 v42, v42
	v_rcp_f32_e32 v43, v43
	v_rcp_f32_e32 v36, v36
	v_rcp_f32_e32 v37, v37
	v_pk_mul_f32 v[32:33], v[32:33], v[48:49] op_sel_hi:[1,0]
	v_pk_mul_f32 v[34:35], v[38:39], v[34:35]
	v_pk_mul_f32 v[32:33], v[32:33], v[42:43]
	v_pk_mul_f32 v[24:25], v[28:29], v[24:25]
	v_cvt_pk_bf16_f32 v42, v32, v33
	v_pk_mul_f32 v[32:33], v[34:35], v[48:49] op_sel_hi:[1,0]
	v_mul_f32_e32 v34, 0xbfb8aa3b, v134
	v_pk_mul_f32 v[32:33], v[32:33], v[36:37]
	v_pk_mul_f32 v[36:37], v[28:29], v[34:35] op_sel_hi:[1,0]
	v_pk_mul_f32 v[28:29], v[30:31], v[34:35] op_sel_hi:[1,0]
	v_exp_f32_e32 v36, v36
	v_exp_f32_e32 v28, v28
	v_exp_f32_e32 v29, v29
	v_exp_f32_e32 v37, v37
	v_cvt_pk_bf16_f32 v43, v32, v33
	v_add_u32_e32 v32, 0x90, v147
	v_pk_add_f32 v[28:29], v[28:29], 1.0 op_sel_hi:[1,0]
	v_mad_i64_i32 v[32:33], s[14:15], v32, s18, v[112:113]
	v_rcp_f32_e32 v28, v28
	v_rcp_f32_e32 v29, v29
	v_lshl_add_u64 v[32:33], v[32:33], 0, v[114:115]
	v_pk_add_f32 v[36:37], v[36:37], 1.0 op_sel_hi:[1,0]
	global_store_dwordx4 v[32:33], v[40:43], off
	v_mul_f32_e32 v32, v134, v134
	v_rcp_f32_e32 v36, v36
	v_rcp_f32_e32 v37, v37
	v_pk_mul_f32 v[26:27], v[30:31], v[26:27]
	v_pk_mul_f32 v[30:31], v[20:21], v[34:35] op_sel_hi:[1,0]
	v_pk_mul_f32 v[26:27], v[26:27], v[32:33] op_sel_hi:[1,0]
	v_exp_f32_e32 v30, v30
	v_exp_f32_e32 v31, v31
	v_pk_mul_f32 v[26:27], v[26:27], v[28:29]
	v_pk_mul_f32 v[28:29], v[22:23], v[34:35] op_sel_hi:[1,0]
	v_pk_mul_f32 v[24:25], v[24:25], v[32:33] op_sel_hi:[1,0]
	v_exp_f32_e32 v28, v28
	v_exp_f32_e32 v29, v29
	v_pk_mul_f32 v[24:25], v[24:25], v[36:37]
	v_pk_mul_f32 v[16:17], v[20:21], v[16:17]
	v_cvt_pk_bf16_f32 v24, v24, v25
	v_cvt_pk_bf16_f32 v25, v26, v27
	v_pk_add_f32 v[26:27], v[30:31], 1.0 op_sel_hi:[1,0]
	v_pk_add_f32 v[20:21], v[28:29], 1.0 op_sel_hi:[1,0]
	v_rcp_f32_e32 v26, v26
	v_rcp_f32_e32 v27, v27
	v_rcp_f32_e32 v20, v20
	v_rcp_f32_e32 v21, v21
	v_pk_mul_f32 v[16:17], v[16:17], v[32:33] op_sel_hi:[1,0]
	v_pk_mul_f32 v[18:19], v[22:23], v[18:19]
	v_pk_mul_f32 v[16:17], v[16:17], v[26:27]
	v_pk_mul_f32 v[8:9], v[12:13], v[8:9]
	v_cvt_pk_bf16_f32 v26, v16, v17
	v_pk_mul_f32 v[16:17], v[18:19], v[32:33] op_sel_hi:[1,0]
	v_mul_f32_e32 v18, 0xbfb8aa3b, v135
	v_pk_mul_f32 v[16:17], v[16:17], v[20:21]
	v_pk_mul_f32 v[20:21], v[12:13], v[18:19] op_sel_hi:[1,0]
	v_pk_mul_f32 v[12:13], v[14:15], v[18:19] op_sel_hi:[1,0]
	v_exp_f32_e32 v20, v20
	v_exp_f32_e32 v12, v12
	v_exp_f32_e32 v13, v13
	v_exp_f32_e32 v21, v21
	v_cvt_pk_bf16_f32 v27, v16, v17
	v_add_u32_e32 v16, 0xa0, v147
	v_pk_add_f32 v[12:13], v[12:13], 1.0 op_sel_hi:[1,0]
	v_mad_i64_i32 v[16:17], s[14:15], v16, s18, v[112:113]
	v_rcp_f32_e32 v12, v12
	v_rcp_f32_e32 v13, v13
	v_lshl_add_u64 v[16:17], v[16:17], 0, v[114:115]
	v_pk_add_f32 v[20:21], v[20:21], 1.0 op_sel_hi:[1,0]
	global_store_dwordx4 v[16:17], v[24:27], off
	v_mul_f32_e32 v16, v135, v135
	v_rcp_f32_e32 v20, v20
	v_rcp_f32_e32 v21, v21
	v_pk_mul_f32 v[10:11], v[14:15], v[10:11]
	v_pk_mul_f32 v[14:15], v[4:5], v[18:19] op_sel_hi:[1,0]
	v_pk_mul_f32 v[10:11], v[10:11], v[16:17] op_sel_hi:[1,0]
	v_exp_f32_e32 v14, v14
	v_exp_f32_e32 v15, v15
	v_pk_mul_f32 v[10:11], v[10:11], v[12:13]
	v_pk_mul_f32 v[12:13], v[6:7], v[18:19] op_sel_hi:[1,0]
	v_pk_mul_f32 v[8:9], v[8:9], v[16:17] op_sel_hi:[1,0]
	v_exp_f32_e32 v12, v12
	v_exp_f32_e32 v13, v13
	v_pk_mul_f32 v[8:9], v[8:9], v[20:21]
	v_pk_mul_f32 v[0:1], v[4:5], v[0:1]
	v_cvt_pk_bf16_f32 v8, v8, v9
	v_cvt_pk_bf16_f32 v9, v10, v11
	v_pk_add_f32 v[10:11], v[14:15], 1.0 op_sel_hi:[1,0]
	v_pk_add_f32 v[4:5], v[12:13], 1.0 op_sel_hi:[1,0]
	v_rcp_f32_e32 v10, v10
	v_rcp_f32_e32 v11, v11
	v_rcp_f32_e32 v4, v4
	v_rcp_f32_e32 v5, v5
	v_pk_mul_f32 v[0:1], v[0:1], v[16:17] op_sel_hi:[1,0]
	v_pk_mul_f32 v[2:3], v[6:7], v[2:3]
	v_pk_mul_f32 v[0:1], v[0:1], v[10:11]
	s_andn2_b64 vcc, exec, s[40:41]
	v_cvt_pk_bf16_f32 v10, v0, v1
	v_pk_mul_f32 v[0:1], v[2:3], v[16:17] op_sel_hi:[1,0]
	s_nop 0
	v_pk_mul_f32 v[0:1], v[0:1], v[4:5]
	s_nop 0
	v_cvt_pk_bf16_f32 v11, v0, v1
	v_add_u32_e32 v0, 0xb0, v147
	v_mad_i64_i32 v[0:1], s[14:15], v0, s18, v[112:113]
	v_lshl_add_u64 v[0:1], v[0:1], 0, v[114:115]
	s_mov_b64 s[14:15], -1
	global_store_dwordx4 v[0:1], v[8:11], off
	s_cbranch_vccnz .LBB0_455
	s_and_b64 vcc, exec, s[36:37]
	s_cbranch_vccnz .LBB0_467
	s_lshl_b32 s14, s42, 8
	s_ashr_i32 s15, s14, 31
	v_lshl_add_u64 v[0:1], s[14:15], 2, v[130:131]
	global_load_dword v140, v[0:1], off

.LBB0_481:
	s_add_u32 s14, s46, 0xfffc0080
	s_addc_u32 s15, s47, -1
	s_add_i32 s60, 0, 0x10000
	s_cmp_eq_u32 s49, 12
	s_cselect_b32 s15, s31, s15
	s_cselect_b32 s14, s41, s14
	v_add_u32_e32 v135, s60, v143
	s_cselect_b32 s51, s13, s17
	s_cselect_b32 s50, s48, s16
	s_add_i32 s61, 0, 0x14000
	ds_read_b128 v[136:139], v135
	ds_read_b128 v[148:151], v135 offset:1024
	ds_read_b128 v[152:155], v135 offset:2048
	ds_read_b128 v[156:159], v135 offset:3072
	v_add_u32_e32 v135, s61, v143
	ds_read_b128 v[160:163], v135
	ds_read_b128 v[164:167], v135 offset:1024
	ds_read_b128 v[168:171], v135 offset:2048
	ds_read_b128 v[172:175], v135 offset:3072
	v_lshl_add_u64 v[140:141], s[46:47], 0, v[184:185]
	s_add_i32 m0, s19, 0xc000
	ds_read_b128 v[176:179], v147
	ds_read_b128 v[180:183], v147 offset:1024
	ds_read_b128 v[194:197], v147 offset:2048
	ds_read_b128 v[198:201], v147 offset:3072
	ds_read_b128 v[202:205], v147 offset:4096
	ds_read_b128 v[206:209], v147 offset:5120
	ds_read_b128 v[210:213], v147 offset:6144
	ds_read_b128 v[214:217], v147 offset:7168
	global_load_lds_dwordx4 v[140:141], off
	v_lshl_add_u64 v[140:141], v[140:141], 0, s[34:35]
	s_add_i32 m0, s19, 0xe000
	s_nop 0
	global_load_lds_dwordx4 v[140:141], off
	s_waitcnt vmcnt(10)
	s_waitcnt lgkmcnt(0)
	s_barrier
	s_setprio 1
	s_waitcnt lgkmcnt(0)
	v_mfma_f32_16x16x32_bf16 v[124:127], v[136:139], v[176:179], v[124:127]
	v_mfma_f32_16x16x32_bf16 v[116:119], v[152:155], v[176:179], v[116:119]
	v_mfma_f32_16x16x32_bf16 v[108:111], v[136:139], v[194:197], v[108:111]
	v_mfma_f32_16x16x32_bf16 v[100:103], v[152:155], v[194:197], v[100:103]
	v_mfma_f32_16x16x32_bf16 v[92:95], v[136:139], v[202:205], v[92:95]
	v_mfma_f32_16x16x32_bf16 v[84:87], v[152:155], v[202:205], v[84:87]
	v_mfma_f32_16x16x32_bf16 v[76:79], v[136:139], v[210:213], v[76:79]
	v_mfma_f32_16x16x32_bf16 v[68:71], v[152:155], v[210:213], v[68:71]
	v_mfma_f32_16x16x32_bf16 v[124:127], v[148:151], v[180:183], v[124:127]
	v_mfma_f32_16x16x32_bf16 v[116:119], v[156:159], v[180:183], v[116:119]
	v_mfma_f32_16x16x32_bf16 v[108:111], v[148:151], v[198:201], v[108:111]
	v_mfma_f32_16x16x32_bf16 v[100:103], v[156:159], v[198:201], v[100:103]
	v_mfma_f32_16x16x32_bf16 v[92:95], v[148:151], v[206:209], v[92:95]
	v_mfma_f32_16x16x32_bf16 v[84:87], v[156:159], v[206:209], v[84:87]
	v_mfma_f32_16x16x32_bf16 v[76:79], v[148:151], v[214:217], v[76:79]
	v_mfma_f32_16x16x32_bf16 v[68:71], v[156:159], v[214:217], v[68:71]
	s_setprio 0
	s_setprio 1
	v_mfma_f32_16x16x32_bf16 v[120:123], v[160:163], v[176:179], v[120:123]
	v_mfma_f32_16x16x32_bf16 v[112:115], v[168:171], v[176:179], v[112:115]
	v_mfma_f32_16x16x32_bf16 v[104:107], v[160:163], v[194:197], v[104:107]
	v_mfma_f32_16x16x32_bf16 v[96:99], v[168:171], v[194:197], v[96:99]
	v_mfma_f32_16x16x32_bf16 v[88:91], v[160:163], v[202:205], v[88:91]
	v_mfma_f32_16x16x32_bf16 v[80:83], v[168:171], v[202:205], v[80:83]
	v_mfma_f32_16x16x32_bf16 v[72:75], v[160:163], v[210:213], v[72:75]
	v_mfma_f32_16x16x32_bf16 v[64:67], v[168:171], v[210:213], v[64:67]
	v_mfma_f32_16x16x32_bf16 v[120:123], v[164:167], v[180:183], v[120:123]
	v_mfma_f32_16x16x32_bf16 v[112:115], v[172:175], v[180:183], v[112:115]
	v_mfma_f32_16x16x32_bf16 v[104:107], v[164:167], v[198:201], v[104:107]
	v_mfma_f32_16x16x32_bf16 v[96:99], v[172:175], v[198:201], v[96:99]
	v_mfma_f32_16x16x32_bf16 v[88:91], v[164:167], v[206:209], v[88:91]
	v_mfma_f32_16x16x32_bf16 v[80:83], v[172:175], v[206:209], v[80:83]
	v_mfma_f32_16x16x32_bf16 v[72:75], v[164:167], v[214:217], v[72:75]
	v_mfma_f32_16x16x32_bf16 v[64:67], v[172:175], v[214:217], v[64:67]
	s_setprio 0
	s_barrier
	v_lshl_add_u64 v[140:141], s[50:51], 0, v[128:129]
	s_add_i32 s50, s60, s6
	s_mov_b32 m0, s50
	ds_read_b128 v[176:179], v147 offset:16384
	ds_read_b128 v[180:183], v147 offset:17408
	ds_read_b128 v[194:197], v147 offset:18432
	ds_read_b128 v[198:201], v147 offset:19456
	ds_read_b128 v[202:205], v147 offset:20480
	ds_read_b128 v[206:209], v147 offset:21504
	ds_read_b128 v[210:213], v147 offset:22528
	ds_read_b128 v[214:217], v147 offset:23552
	global_load_lds_dwordx4 v[140:141], off
	v_lshl_add_u64 v[218:219], v[140:141], 0, s[34:35]
	s_add_i32 m0, s50, 0x2000
	s_add_i32 s50, s61, s6
	global_load_lds_dwordx4 v[218:219], off
	v_lshl_add_u64 v[218:219], v[140:141], 0, s[92:93]
	s_mov_b32 m0, s50
	s_nop 0
	global_load_lds_dwordx4 v[218:219], off
	v_lshl_add_u64 v[218:219], v[140:141], 0, s[52:53]
	s_add_i32 m0, s50, 0x2000
	s_nop 0
	global_load_lds_dwordx4 v[218:219], off
	v_lshl_add_u64 v[218:219], s[14:15], 0, v[130:131]
	s_mov_b32 m0, s19
	v_lshl_add_u64 v[220:221], v[218:219], 0, s[34:35]
	global_load_lds_dwordx4 v[218:219], off
	s_mov_b32 m0, s20
	s_nop 0
	global_load_lds_dwordx4 v[220:221], off
	s_waitcnt vmcnt(14)
	s_waitcnt lgkmcnt(0)
	s_barrier
	s_setprio 1
	s_waitcnt lgkmcnt(0)
	v_mfma_f32_16x16x32_bf16 v[60:63], v[136:139], v[176:179], v[60:63]
	v_mfma_f32_16x16x32_bf16 v[52:55], v[152:155], v[176:179], v[52:55]
	v_mfma_f32_16x16x32_bf16 v[44:47], v[136:139], v[194:197], v[44:47]
	v_mfma_f32_16x16x32_bf16 v[36:39], v[152:155], v[194:197], v[36:39]
	v_mfma_f32_16x16x32_bf16 v[28:31], v[136:139], v[202:205], v[28:31]
	v_mfma_f32_16x16x32_bf16 v[20:23], v[152:155], v[202:205], v[20:23]
	v_mfma_f32_16x16x32_bf16 v[12:15], v[136:139], v[210:213], v[12:15]
	v_mfma_f32_16x16x32_bf16 v[4:7], v[152:155], v[210:213], v[4:7]
	v_mfma_f32_16x16x32_bf16 v[60:63], v[148:151], v[180:183], v[60:63]
	v_mfma_f32_16x16x32_bf16 v[52:55], v[156:159], v[180:183], v[52:55]
	v_mfma_f32_16x16x32_bf16 v[44:47], v[148:151], v[198:201], v[44:47]
	v_mfma_f32_16x16x32_bf16 v[36:39], v[156:159], v[198:201], v[36:39]
	v_mfma_f32_16x16x32_bf16 v[28:31], v[148:151], v[206:209], v[28:31]
	v_mfma_f32_16x16x32_bf16 v[20:23], v[156:159], v[206:209], v[20:23]
	v_mfma_f32_16x16x32_bf16 v[12:15], v[148:151], v[214:217], v[12:15]
	v_mfma_f32_16x16x32_bf16 v[4:7], v[156:159], v[214:217], v[4:7]
	s_setprio 0
	s_setprio 1
	v_mfma_f32_16x16x32_bf16 v[56:59], v[160:163], v[176:179], v[56:59]
	v_mfma_f32_16x16x32_bf16 v[48:51], v[168:171], v[176:179], v[48:51]
	v_mfma_f32_16x16x32_bf16 v[40:43], v[160:163], v[194:197], v[40:43]
	v_mfma_f32_16x16x32_bf16 v[32:35], v[168:171], v[194:197], v[32:35]
	v_mfma_f32_16x16x32_bf16 v[24:27], v[160:163], v[202:205], v[24:27]
	v_mfma_f32_16x16x32_bf16 v[16:19], v[168:171], v[202:205], v[16:19]
	v_mfma_f32_16x16x32_bf16 v[8:11], v[160:163], v[210:213], v[8:11]
	v_mfma_f32_16x16x32_bf16 v[0:3], v[168:171], v[210:213], v[0:3]
	v_mfma_f32_16x16x32_bf16 v[56:59], v[164:167], v[180:183], v[56:59]
	v_mfma_f32_16x16x32_bf16 v[48:51], v[172:175], v[180:183], v[48:51]
	v_mfma_f32_16x16x32_bf16 v[40:43], v[164:167], v[198:201], v[40:43]
	v_mfma_f32_16x16x32_bf16 v[32:35], v[172:175], v[198:201], v[32:35]
	v_mfma_f32_16x16x32_bf16 v[24:27], v[164:167], v[206:209], v[24:27]
	v_mfma_f32_16x16x32_bf16 v[16:19], v[172:175], v[206:209], v[16:19]
	v_mfma_f32_16x16x32_bf16 v[8:11], v[164:167], v[214:217], v[8:11]
	v_mfma_f32_16x16x32_bf16 v[0:3], v[172:175], v[214:217], v[0:3]
	s_setprio 0
	s_barrier
	s_add_i32 s14, 0, 0x18000
	v_add_u32_e32 v135, s14, v143
	s_add_i32 s15, 0, 0x1c000
	ds_read_b128 v[136:139], v135
	ds_read_b128 v[148:151], v135 offset:1024
	ds_read_b128 v[152:155], v135 offset:2048
	ds_read_b128 v[156:159], v135 offset:3072
	v_add_u32_e32 v135, s15, v143
	ds_read_b128 v[160:163], v135
	ds_read_b128 v[164:167], v135 offset:1024
	ds_read_b128 v[168:171], v135 offset:2048
	ds_read_b128 v[172:175], v135 offset:3072
	s_mov_b32 m0, s24
	v_lshl_add_u64 v[220:221], v[218:219], 0, s[92:93]
	ds_read_b128 v[176:179], v147 offset:32768
	ds_read_b128 v[180:183], v147 offset:33792
	ds_read_b128 v[194:197], v147 offset:34816
	ds_read_b128 v[198:201], v147 offset:35840
	ds_read_b128 v[202:205], v147 offset:36864
	ds_read_b128 v[206:209], v147 offset:37888
	ds_read_b128 v[210:213], v147 offset:38912
	ds_read_b128 v[214:217], v147 offset:39936
	global_load_lds_dwordx4 v[220:221], off
	v_lshl_add_u64 v[220:221], v[218:219], 0, s[52:53]
	s_mov_b32 m0, s25
	s_nop 0
	global_load_lds_dwordx4 v[220:221], off
	s_waitcnt vmcnt(10)
	s_waitcnt lgkmcnt(0)
	s_barrier
	s_setprio 1
	s_waitcnt lgkmcnt(0)
	v_mfma_f32_16x16x32_bf16 v[124:127], v[136:139], v[176:179], v[124:127]
	v_mfma_f32_16x16x32_bf16 v[116:119], v[152:155], v[176:179], v[116:119]
	v_mfma_f32_16x16x32_bf16 v[108:111], v[136:139], v[194:197], v[108:111]
	v_mfma_f32_16x16x32_bf16 v[100:103], v[152:155], v[194:197], v[100:103]
	v_mfma_f32_16x16x32_bf16 v[92:95], v[136:139], v[202:205], v[92:95]
	v_mfma_f32_16x16x32_bf16 v[84:87], v[152:155], v[202:205], v[84:87]
	v_mfma_f32_16x16x32_bf16 v[76:79], v[136:139], v[210:213], v[76:79]
	v_mfma_f32_16x16x32_bf16 v[68:71], v[152:155], v[210:213], v[68:71]
	v_mfma_f32_16x16x32_bf16 v[124:127], v[148:151], v[180:183], v[124:127]
	v_mfma_f32_16x16x32_bf16 v[116:119], v[156:159], v[180:183], v[116:119]
	v_mfma_f32_16x16x32_bf16 v[108:111], v[148:151], v[198:201], v[108:111]
	v_mfma_f32_16x16x32_bf16 v[100:103], v[156:159], v[198:201], v[100:103]
	v_mfma_f32_16x16x32_bf16 v[92:95], v[148:151], v[206:209], v[92:95]
	v_mfma_f32_16x16x32_bf16 v[84:87], v[156:159], v[206:209], v[84:87]
	v_mfma_f32_16x16x32_bf16 v[76:79], v[148:151], v[214:217], v[76:79]
	v_mfma_f32_16x16x32_bf16 v[68:71], v[156:159], v[214:217], v[68:71]
	s_setprio 0
	s_setprio 1
	v_mfma_f32_16x16x32_bf16 v[120:123], v[160:163], v[176:179], v[120:123]
	v_mfma_f32_16x16x32_bf16 v[112:115], v[168:171], v[176:179], v[112:115]
	v_mfma_f32_16x16x32_bf16 v[104:107], v[160:163], v[194:197], v[104:107]
	v_mfma_f32_16x16x32_bf16 v[96:99], v[168:171], v[194:197], v[96:99]
	v_mfma_f32_16x16x32_bf16 v[88:91], v[160:163], v[202:205], v[88:91]
	v_mfma_f32_16x16x32_bf16 v[80:83], v[168:171], v[202:205], v[80:83]
	v_mfma_f32_16x16x32_bf16 v[72:75], v[160:163], v[210:213], v[72:75]
	v_mfma_f32_16x16x32_bf16 v[64:67], v[168:171], v[210:213], v[64:67]
	v_mfma_f32_16x16x32_bf16 v[120:123], v[164:167], v[180:183], v[120:123]
	v_mfma_f32_16x16x32_bf16 v[112:115], v[172:175], v[180:183], v[112:115]
	v_mfma_f32_16x16x32_bf16 v[104:107], v[164:167], v[198:201], v[104:107]
	v_mfma_f32_16x16x32_bf16 v[96:99], v[172:175], v[198:201], v[96:99]
	v_mfma_f32_16x16x32_bf16 v[88:91], v[164:167], v[206:209], v[88:91]
	v_mfma_f32_16x16x32_bf16 v[80:83], v[172:175], v[206:209], v[80:83]
	v_mfma_f32_16x16x32_bf16 v[72:75], v[164:167], v[214:217], v[72:75]
	v_mfma_f32_16x16x32_bf16 v[64:67], v[172:175], v[214:217], v[64:67]
	s_setprio 0
	s_barrier
	s_add_i32 s14, s14, s6
	v_lshl_add_u64 v[220:221], v[140:141], 0, s[56:57]
	s_mov_b32 m0, s14
	ds_read_b128 v[176:179], v147 offset:49152
	ds_read_b128 v[180:183], v147 offset:50176
	ds_read_b128 v[194:197], v147 offset:51200
	ds_read_b128 v[198:201], v147 offset:52224
	ds_read_b128 v[202:205], v147 offset:53248
	ds_read_b128 v[206:209], v147 offset:54272
	ds_read_b128 v[210:213], v147 offset:55296
	ds_read_b128 v[214:217], v147 offset:56320
	global_load_lds_dwordx4 v[220:221], off
	v_lshl_add_u64 v[220:221], v[140:141], 0, s[96:97]
	s_add_i32 m0, s14, 0x2000
	s_add_i32 s14, s15, s6
	global_load_lds_dwordx4 v[220:221], off
	v_lshl_add_u64 v[220:221], v[140:141], 0, s[88:89]
	s_mov_b32 m0, s14
	v_lshl_add_u64 v[140:141], v[140:141], 0, s[68:69]
	global_load_lds_dwordx4 v[220:221], off
	s_add_i32 m0, s14, 0x2000
	s_nop 0
	global_load_lds_dwordx4 v[140:141], off
	v_lshl_add_u64 v[140:141], v[218:219], 0, s[56:57]
	s_mov_b32 m0, s26
	s_nop 0
	global_load_lds_dwordx4 v[140:141], off
	v_lshl_add_u64 v[140:141], v[218:219], 0, s[96:97]
	s_mov_b32 m0, s27
	s_nop 0
	global_load_lds_dwordx4 v[140:141], off
	s_waitcnt vmcnt(14)
	s_waitcnt lgkmcnt(0)
	s_barrier
	s_setprio 1
	s_waitcnt lgkmcnt(0)
	v_mfma_f32_16x16x32_bf16 v[60:63], v[136:139], v[176:179], v[60:63]
	v_mfma_f32_16x16x32_bf16 v[52:55], v[152:155], v[176:179], v[52:55]
	v_mfma_f32_16x16x32_bf16 v[44:47], v[136:139], v[194:197], v[44:47]
	v_mfma_f32_16x16x32_bf16 v[36:39], v[152:155], v[194:197], v[36:39]
	v_mfma_f32_16x16x32_bf16 v[28:31], v[136:139], v[202:205], v[28:31]
	v_mfma_f32_16x16x32_bf16 v[20:23], v[152:155], v[202:205], v[20:23]
	v_mfma_f32_16x16x32_bf16 v[12:15], v[136:139], v[210:213], v[12:15]
	v_mfma_f32_16x16x32_bf16 v[4:7], v[152:155], v[210:213], v[4:7]
	v_mfma_f32_16x16x32_bf16 v[60:63], v[148:151], v[180:183], v[60:63]
	v_mfma_f32_16x16x32_bf16 v[52:55], v[156:159], v[180:183], v[52:55]
	v_mfma_f32_16x16x32_bf16 v[44:47], v[148:151], v[198:201], v[44:47]
	v_mfma_f32_16x16x32_bf16 v[36:39], v[156:159], v[198:201], v[36:39]
	v_mfma_f32_16x16x32_bf16 v[28:31], v[148:151], v[206:209], v[28:31]
	v_mfma_f32_16x16x32_bf16 v[20:23], v[156:159], v[206:209], v[20:23]
	v_mfma_f32_16x16x32_bf16 v[12:15], v[148:151], v[214:217], v[12:15]
	v_mfma_f32_16x16x32_bf16 v[4:7], v[156:159], v[214:217], v[4:7]
	s_setprio 0
	s_setprio 1
	v_mfma_f32_16x16x32_bf16 v[56:59], v[160:163], v[176:179], v[56:59]
	v_mfma_f32_16x16x32_bf16 v[48:51], v[168:171], v[176:179], v[48:51]
	v_mfma_f32_16x16x32_bf16 v[40:43], v[160:163], v[194:197], v[40:43]
	v_mfma_f32_16x16x32_bf16 v[32:35], v[168:171], v[194:197], v[32:35]
	v_mfma_f32_16x16x32_bf16 v[24:27], v[160:163], v[202:205], v[24:27]
	v_mfma_f32_16x16x32_bf16 v[16:19], v[168:171], v[202:205], v[16:19]
	v_mfma_f32_16x16x32_bf16 v[8:11], v[160:163], v[210:213], v[8:11]
	v_mfma_f32_16x16x32_bf16 v[0:3], v[168:171], v[210:213], v[0:3]
	v_mfma_f32_16x16x32_bf16 v[56:59], v[164:167], v[180:183], v[56:59]
	v_mfma_f32_16x16x32_bf16 v[48:51], v[172:175], v[180:183], v[48:51]
	v_mfma_f32_16x16x32_bf16 v[40:43], v[164:167], v[198:201], v[40:43]
	v_mfma_f32_16x16x32_bf16 v[32:35], v[172:175], v[198:201], v[32:35]
	v_mfma_f32_16x16x32_bf16 v[24:27], v[164:167], v[206:209], v[24:27]
	v_mfma_f32_16x16x32_bf16 v[16:19], v[172:175], v[206:209], v[16:19]
	v_mfma_f32_16x16x32_bf16 v[8:11], v[164:167], v[214:217], v[8:11]
	v_mfma_f32_16x16x32_bf16 v[0:3], v[172:175], v[214:217], v[0:3]
	s_setprio 0
	s_barrier
	s_add_i32 s49, s49, 2
	s_add_u32 s46, s46, 0x100
	s_addc_u32 s47, s47, 0
	s_add_u32 s16, s16, 0x100
	s_addc_u32 s17, s17, 0
	s_cmp_gt_u32 s49, 13
	s_cbranch_scc0 .LBB0_481
	s_and_b64 vcc, exec, s[10:11]
	s_cbranch_vccz .LBB0_484
	v_cvt_f32_u32_e32 v134, v134
	v_fmamk_f32 v134, v134, 0x35800000, v242
	v_rsq_f32_e32 v134, v134
	ds_write_b32 v144, v134
	s_waitcnt lgkmcnt(0)
	s_barrier

.Lnochk484:
	s_mov_b64 s[48:49], 0x84000
	ds_read2_b32 v[150:151], v145 offset1:16
	ds_read2_b32 v[140:141], v145 offset0:32 offset1:48
	ds_read2_b32 v[138:139], v145 offset0:128 offset1:144
	ds_read2_b32 v[136:137], v145 offset0:160 offset1:176
	v_pk_mul_f32 v[120:121], v[124:125], v[120:121]
	s_waitcnt lgkmcnt(0)
	v_mul_f32_e32 v152, 0xbfb8aa3b, v150
	v_pk_mul_f32 v[154:155], v[124:125], v[152:153] op_sel_hi:[1,0]
	v_pk_mul_f32 v[124:125], v[126:127], v[152:153] op_sel_hi:[1,0]
	v_mul_f32_e32 v150, v150, v150
	v_exp_f32_e32 v124, v124
	v_exp_f32_e32 v125, v125
	v_pk_mul_f32 v[122:123], v[126:127], v[122:123]
	v_pk_mul_f32 v[112:113], v[116:117], v[112:113]
	v_pk_mul_f32 v[122:123], v[122:123], v[150:151] op_sel_hi:[1,0]
	v_pk_add_f32 v[124:125], v[124:125], 1.0 op_sel_hi:[1,0]
	v_exp_f32_e32 v154, v154
	v_rcp_f32_e32 v124, v124
	v_rcp_f32_e32 v125, v125
	v_exp_f32_e32 v155, v155
	v_pk_mul_f32 v[114:115], v[118:119], v[114:115]
	v_pk_mul_f32 v[120:121], v[120:121], v[150:151] op_sel_hi:[1,0]
	v_pk_mul_f32 v[122:123], v[122:123], v[124:125]
	v_pk_mul_f32 v[124:125], v[116:117], v[152:153] op_sel_hi:[1,0]
	v_pk_mul_f32 v[116:117], v[118:119], v[152:153] op_sel_hi:[1,0]
	v_exp_f32_e32 v124, v124
	v_exp_f32_e32 v125, v125
	v_exp_f32_e32 v116, v116
	v_exp_f32_e32 v117, v117
	v_pk_add_f32 v[154:155], v[154:155], 1.0 op_sel_hi:[1,0]
	v_pk_add_f32 v[124:125], v[124:125], 1.0 op_sel_hi:[1,0]
	v_rcp_f32_e32 v154, v154
	v_pk_add_f32 v[116:117], v[116:117], 1.0 op_sel_hi:[1,0]
	v_rcp_f32_e32 v155, v155
	v_rcp_f32_e32 v124, v124
	v_rcp_f32_e32 v125, v125
	v_rcp_f32_e32 v116, v116
	v_rcp_f32_e32 v117, v117
	v_pk_mul_f32 v[112:113], v[112:113], v[150:151] op_sel_hi:[1,0]
	v_pk_mul_f32 v[114:115], v[114:115], v[150:151] op_sel_hi:[1,0]
	v_pk_mul_f32 v[120:121], v[120:121], v[154:155]
	v_pk_mul_f32 v[112:113], v[112:113], v[124:125]
	v_pk_mul_f32 v[114:115], v[114:115], v[116:117]
	v_mov_b32_e32 v116, 0
	v_mov_b32_e32 v117, 0
	v_cvt_pk_fp8_f32 v116, v120, v121
	v_cvt_pk_fp8_f32 v117, v112, v113
	v_lshl_add_u32 v148, s30, 8, v142
	v_lshl_or_b32 v134, s29, 7, v146
	v_cvt_pk_fp8_f32 v116, v122, v123 op_sel:[0,0,1]
	v_cvt_pk_fp8_f32 v117, v114, v115 op_sel:[0,0,1]
	v_mov_b64_e32 v[112:113], s[72:73]
	v_ashrrev_i32_e32 v135, 31, v134
	v_mad_i64_i32 v[114:115], s[14:15], v148, s18, v[112:113]
	v_lshl_add_u64 v[114:115], v[114:115], 0, v[134:135]
	global_store_dwordx2 v[114:115], v[116:117], off
	v_mul_f32_e32 v114, 0xbfb8aa3b, v151
	v_pk_mul_f32 v[118:119], v[108:109], v[114:115] op_sel_hi:[1,0]
	v_pk_mul_f32 v[104:105], v[108:109], v[104:105]
	v_pk_mul_f32 v[108:109], v[110:111], v[114:115] op_sel_hi:[1,0]
	v_mul_f32_e32 v116, v151, v151
	v_exp_f32_e32 v108, v108
	v_exp_f32_e32 v109, v109
	v_pk_mul_f32 v[106:107], v[110:111], v[106:107]
	v_pk_mul_f32 v[96:97], v[100:101], v[96:97]
	v_pk_mul_f32 v[106:107], v[106:107], v[116:117] op_sel_hi:[1,0]
	v_pk_add_f32 v[108:109], v[108:109], 1.0 op_sel_hi:[1,0]
	v_exp_f32_e32 v118, v118
	v_rcp_f32_e32 v108, v108
	v_rcp_f32_e32 v109, v109
	v_exp_f32_e32 v119, v119
	v_pk_mul_f32 v[98:99], v[102:103], v[98:99]
	v_pk_mul_f32 v[104:105], v[104:105], v[116:117] op_sel_hi:[1,0]
	v_pk_mul_f32 v[106:107], v[106:107], v[108:109]
	v_pk_mul_f32 v[108:109], v[100:101], v[114:115] op_sel_hi:[1,0]
	v_pk_mul_f32 v[100:101], v[102:103], v[114:115] op_sel_hi:[1,0]
	v_exp_f32_e32 v108, v108
	v_exp_f32_e32 v109, v109
	v_exp_f32_e32 v100, v100
	v_exp_f32_e32 v101, v101
	v_pk_add_f32 v[118:119], v[118:119], 1.0 op_sel_hi:[1,0]
	v_pk_add_f32 v[108:109], v[108:109], 1.0 op_sel_hi:[1,0]
	v_rcp_f32_e32 v118, v118
	v_pk_add_f32 v[100:101], v[100:101], 1.0 op_sel_hi:[1,0]
	v_rcp_f32_e32 v119, v119
	v_rcp_f32_e32 v108, v108
	v_rcp_f32_e32 v109, v109
	v_rcp_f32_e32 v100, v100
	v_rcp_f32_e32 v101, v101
	v_pk_mul_f32 v[96:97], v[96:97], v[116:117] op_sel_hi:[1,0]
	v_pk_mul_f32 v[98:99], v[98:99], v[116:117] op_sel_hi:[1,0]
	v_pk_mul_f32 v[104:105], v[104:105], v[118:119]
	v_pk_mul_f32 v[96:97], v[96:97], v[108:109]
	v_pk_mul_f32 v[98:99], v[98:99], v[100:101]
	v_mov_b32_e32 v100, 0
	v_mov_b32_e32 v101, 0
	v_cvt_pk_fp8_f32 v100, v104, v105
	v_cvt_pk_fp8_f32 v101, v96, v97
	v_or_b32_e32 v96, 16, v148
	v_mad_i64_i32 v[96:97], s[14:15], v96, s18, v[112:113]
	v_cvt_pk_fp8_f32 v100, v106, v107 op_sel:[0,0,1]
	v_cvt_pk_fp8_f32 v101, v98, v99 op_sel:[0,0,1]
	v_lshl_add_u64 v[96:97], v[96:97], 0, v[134:135]
	v_pk_mul_f32 v[88:89], v[92:93], v[88:89]
	v_mul_f32_e32 v98, v140, v140
	global_store_dwordx2 v[96:97], v[100:101], off
	v_mul_f32_e32 v96, 0xbfb8aa3b, v140
	v_pk_mul_f32 v[100:101], v[92:93], v[96:97] op_sel_hi:[1,0]
	v_pk_mul_f32 v[92:93], v[94:95], v[96:97] op_sel_hi:[1,0]
	v_pk_mul_f32 v[90:91], v[94:95], v[90:91]
	v_exp_f32_e32 v92, v92
	v_exp_f32_e32 v93, v93
	v_pk_mul_f32 v[90:91], v[90:91], v[98:99] op_sel_hi:[1,0]
	v_pk_mul_f32 v[80:81], v[84:85], v[80:81]
	v_exp_f32_e32 v100, v100
	v_pk_add_f32 v[92:93], v[92:93], 1.0 op_sel_hi:[1,0]
	v_exp_f32_e32 v101, v101
	v_rcp_f32_e32 v92, v92
	v_rcp_f32_e32 v93, v93
	v_pk_mul_f32 v[82:83], v[86:87], v[82:83]
	v_pk_add_f32 v[100:101], v[100:101], 1.0 op_sel_hi:[1,0]
	v_pk_mul_f32 v[88:89], v[88:89], v[98:99] op_sel_hi:[1,0]
	v_pk_mul_f32 v[90:91], v[90:91], v[92:93]
	v_pk_mul_f32 v[92:93], v[84:85], v[96:97] op_sel_hi:[1,0]
	v_pk_mul_f32 v[84:85], v[86:87], v[96:97] op_sel_hi:[1,0]
	v_exp_f32_e32 v92, v92
	v_exp_f32_e32 v93, v93
	v_exp_f32_e32 v84, v84
	v_exp_f32_e32 v85, v85
	v_rcp_f32_e32 v100, v100
	v_pk_add_f32 v[92:93], v[92:93], 1.0 op_sel_hi:[1,0]
	v_rcp_f32_e32 v101, v101
	v_pk_add_f32 v[84:85], v[84:85], 1.0 op_sel_hi:[1,0]
	v_rcp_f32_e32 v92, v92
	v_rcp_f32_e32 v93, v93
	v_rcp_f32_e32 v84, v84
	v_rcp_f32_e32 v85, v85
	v_pk_mul_f32 v[80:81], v[80:81], v[98:99] op_sel_hi:[1,0]
	v_pk_mul_f32 v[82:83], v[82:83], v[98:99] op_sel_hi:[1,0]
	v_pk_mul_f32 v[88:89], v[88:89], v[100:101]
	v_pk_mul_f32 v[80:81], v[80:81], v[92:93]
	v_pk_mul_f32 v[82:83], v[82:83], v[84:85]
	v_mov_b32_e32 v84, 0
	v_mov_b32_e32 v85, 0
	v_cvt_pk_fp8_f32 v84, v88, v89
	v_cvt_pk_fp8_f32 v85, v80, v81
	v_or_b32_e32 v80, 32, v148
	v_mad_i64_i32 v[80:81], s[14:15], v80, s18, v[112:113]
	v_cvt_pk_fp8_f32 v84, v90, v91 op_sel:[0,0,1]
	v_cvt_pk_fp8_f32 v85, v82, v83 op_sel:[0,0,1]
	v_lshl_add_u64 v[80:81], v[80:81], 0, v[134:135]
	v_pk_mul_f32 v[72:73], v[76:77], v[72:73]
	v_mul_f32_e32 v82, v141, v141
	global_store_dwordx2 v[80:81], v[84:85], off
	v_mul_f32_e32 v80, 0xbfb8aa3b, v141
	v_pk_mul_f32 v[84:85], v[76:77], v[80:81] op_sel_hi:[1,0]
	v_pk_mul_f32 v[76:77], v[78:79], v[80:81] op_sel_hi:[1,0]
	v_pk_mul_f32 v[74:75], v[78:79], v[74:75]
	v_exp_f32_e32 v76, v76
	v_exp_f32_e32 v77, v77
	v_pk_mul_f32 v[74:75], v[74:75], v[82:83] op_sel_hi:[1,0]
	v_pk_mul_f32 v[64:65], v[68:69], v[64:65]
	v_exp_f32_e32 v84, v84
	v_pk_add_f32 v[76:77], v[76:77], 1.0 op_sel_hi:[1,0]
	v_exp_f32_e32 v85, v85
	v_rcp_f32_e32 v76, v76
	v_rcp_f32_e32 v77, v77
	v_pk_mul_f32 v[66:67], v[70:71], v[66:67]
	v_pk_add_f32 v[84:85], v[84:85], 1.0 op_sel_hi:[1,0]
	v_pk_mul_f32 v[72:73], v[72:73], v[82:83] op_sel_hi:[1,0]
	v_pk_mul_f32 v[74:75], v[74:75], v[76:77]
	v_pk_mul_f32 v[76:77], v[68:69], v[80:81] op_sel_hi:[1,0]
	v_pk_mul_f32 v[68:69], v[70:71], v[80:81] op_sel_hi:[1,0]
	v_exp_f32_e32 v76, v76
	v_exp_f32_e32 v77, v77
	v_exp_f32_e32 v68, v68
	v_exp_f32_e32 v69, v69
	v_rcp_f32_e32 v84, v84
	v_pk_add_f32 v[76:77], v[76:77], 1.0 op_sel_hi:[1,0]
	v_rcp_f32_e32 v85, v85
	v_pk_add_f32 v[68:69], v[68:69], 1.0 op_sel_hi:[1,0]
	v_rcp_f32_e32 v76, v76
	v_rcp_f32_e32 v77, v77
	v_rcp_f32_e32 v68, v68
	v_rcp_f32_e32 v69, v69
	v_pk_mul_f32 v[64:65], v[64:65], v[82:83] op_sel_hi:[1,0]
	v_pk_mul_f32 v[66:67], v[66:67], v[82:83] op_sel_hi:[1,0]
	v_pk_mul_f32 v[72:73], v[72:73], v[84:85]
	v_pk_mul_f32 v[64:65], v[64:65], v[76:77]
	v_pk_mul_f32 v[66:67], v[66:67], v[68:69]
	v_mov_b32_e32 v68, 0
	v_mov_b32_e32 v69, 0
	v_cvt_pk_fp8_f32 v68, v72, v73
	v_cvt_pk_fp8_f32 v69, v64, v65
	v_or_b32_e32 v64, 48, v148
	v_mad_i64_i32 v[64:65], s[14:15], v64, s18, v[112:113]
	v_cvt_pk_fp8_f32 v68, v74, v75 op_sel:[0,0,1]
	v_cvt_pk_fp8_f32 v69, v66, v67 op_sel:[0,0,1]
	v_lshl_add_u64 v[64:65], v[64:65], 0, v[134:135]
	v_pk_mul_f32 v[56:57], v[60:61], v[56:57]
	v_mul_f32_e32 v66, v138, v138
	global_store_dwordx2 v[64:65], v[68:69], off
	v_add_u32_e32 v65, 0x80, v148
	v_mul_f32_e32 v64, 0xbfb8aa3b, v138
	v_pk_mul_f32 v[68:69], v[60:61], v[64:65] op_sel_hi:[1,0]
	v_pk_mul_f32 v[60:61], v[62:63], v[64:65] op_sel_hi:[1,0]
	v_pk_mul_f32 v[58:59], v[62:63], v[58:59]
	v_exp_f32_e32 v60, v60
	v_exp_f32_e32 v61, v61
	v_pk_mul_f32 v[58:59], v[58:59], v[66:67] op_sel_hi:[1,0]
	v_pk_mul_f32 v[48:49], v[52:53], v[48:49]
	v_exp_f32_e32 v68, v68
	v_pk_add_f32 v[60:61], v[60:61], 1.0 op_sel_hi:[1,0]
	v_exp_f32_e32 v69, v69
	v_rcp_f32_e32 v60, v60
	v_rcp_f32_e32 v61, v61
	v_pk_mul_f32 v[50:51], v[54:55], v[50:51]
	v_pk_add_f32 v[68:69], v[68:69], 1.0 op_sel_hi:[1,0]
	v_pk_mul_f32 v[56:57], v[56:57], v[66:67] op_sel_hi:[1,0]
	v_pk_mul_f32 v[58:59], v[58:59], v[60:61]
	v_pk_mul_f32 v[60:61], v[52:53], v[64:65] op_sel_hi:[1,0]
	v_pk_mul_f32 v[52:53], v[54:55], v[64:65] op_sel_hi:[1,0]
	v_exp_f32_e32 v60, v60
	v_exp_f32_e32 v61, v61
	v_exp_f32_e32 v52, v52
	v_exp_f32_e32 v53, v53
	v_rcp_f32_e32 v68, v68
	v_pk_add_f32 v[60:61], v[60:61], 1.0 op_sel_hi:[1,0]
	v_rcp_f32_e32 v69, v69
	v_pk_add_f32 v[52:53], v[52:53], 1.0 op_sel_hi:[1,0]
	v_rcp_f32_e32 v60, v60
	v_rcp_f32_e32 v61, v61
	v_rcp_f32_e32 v52, v52
	v_rcp_f32_e32 v53, v53
	v_pk_mul_f32 v[48:49], v[48:49], v[66:67] op_sel_hi:[1,0]
	v_pk_mul_f32 v[50:51], v[50:51], v[66:67] op_sel_hi:[1,0]
	v_pk_mul_f32 v[56:57], v[56:57], v[68:69]
	v_pk_mul_f32 v[48:49], v[48:49], v[60:61]
	v_pk_mul_f32 v[50:51], v[50:51], v[52:53]
	v_mov_b32_e32 v52, 0
	v_mov_b32_e32 v53, 0
	v_cvt_pk_fp8_f32 v52, v56, v57
	v_cvt_pk_fp8_f32 v53, v48, v49
	v_mad_i64_i32 v[48:49], s[14:15], v65, s18, v[112:113]
	v_cvt_pk_fp8_f32 v52, v58, v59 op_sel:[0,0,1]
	v_cvt_pk_fp8_f32 v53, v50, v51 op_sel:[0,0,1]
	v_lshl_add_u64 v[48:49], v[48:49], 0, v[134:135]
	v_pk_mul_f32 v[40:41], v[44:45], v[40:41]
	v_mul_f32_e32 v50, v139, v139
	global_store_dwordx2 v[48:49], v[52:53], off
	v_mul_f32_e32 v48, 0xbfb8aa3b, v139
	v_pk_mul_f32 v[52:53], v[44:45], v[48:49] op_sel_hi:[1,0]
	v_pk_mul_f32 v[44:45], v[46:47], v[48:49] op_sel_hi:[1,0]
	v_pk_mul_f32 v[42:43], v[46:47], v[42:43]
	v_exp_f32_e32 v44, v44
	v_exp_f32_e32 v45, v45
	v_pk_mul_f32 v[42:43], v[42:43], v[50:51] op_sel_hi:[1,0]
	v_pk_mul_f32 v[32:33], v[36:37], v[32:33]
	v_exp_f32_e32 v52, v52
	v_pk_add_f32 v[44:45], v[44:45], 1.0 op_sel_hi:[1,0]
	v_exp_f32_e32 v53, v53
	v_rcp_f32_e32 v44, v44
	v_rcp_f32_e32 v45, v45
	v_pk_mul_f32 v[34:35], v[38:39], v[34:35]
	v_pk_add_f32 v[52:53], v[52:53], 1.0 op_sel_hi:[1,0]
	v_pk_mul_f32 v[40:41], v[40:41], v[50:51] op_sel_hi:[1,0]
	v_pk_mul_f32 v[42:43], v[42:43], v[44:45]
	v_pk_mul_f32 v[44:45], v[36:37], v[48:49] op_sel_hi:[1,0]
	v_pk_mul_f32 v[36:37], v[38:39], v[48:49] op_sel_hi:[1,0]
	v_exp_f32_e32 v44, v44
	v_exp_f32_e32 v45, v45
	v_exp_f32_e32 v36, v36
	v_exp_f32_e32 v37, v37
	v_rcp_f32_e32 v52, v52
	v_pk_add_f32 v[44:45], v[44:45], 1.0 op_sel_hi:[1,0]
	v_rcp_f32_e32 v53, v53
	v_pk_add_f32 v[36:37], v[36:37], 1.0 op_sel_hi:[1,0]
	v_rcp_f32_e32 v44, v44
	v_rcp_f32_e32 v45, v45
	v_rcp_f32_e32 v36, v36
	v_rcp_f32_e32 v37, v37
	v_pk_mul_f32 v[32:33], v[32:33], v[50:51] op_sel_hi:[1,0]
	v_pk_mul_f32 v[34:35], v[34:35], v[50:51] op_sel_hi:[1,0]
	v_pk_mul_f32 v[40:41], v[40:41], v[52:53]
	v_pk_mul_f32 v[32:33], v[32:33], v[44:45]
	v_pk_mul_f32 v[34:35], v[34:35], v[36:37]
	v_mov_b32_e32 v36, 0
	v_mov_b32_e32 v37, 0
	v_cvt_pk_fp8_f32 v36, v40, v41
	v_cvt_pk_fp8_f32 v37, v32, v33
	v_add_u32_e32 v32, 0x90, v148
	v_mad_i64_i32 v[32:33], s[14:15], v32, s18, v[112:113]
	v_cvt_pk_fp8_f32 v36, v42, v43 op_sel:[0,0,1]
	v_cvt_pk_fp8_f32 v37, v34, v35 op_sel:[0,0,1]
	v_lshl_add_u64 v[32:33], v[32:33], 0, v[134:135]
	v_pk_mul_f32 v[24:25], v[28:29], v[24:25]
	v_mul_f32_e32 v34, v136, v136
	global_store_dwordx2 v[32:33], v[36:37], off
	v_mul_f32_e32 v32, 0xbfb8aa3b, v136
	v_pk_mul_f32 v[36:37], v[28:29], v[32:33] op_sel_hi:[1,0]
	v_pk_mul_f32 v[28:29], v[30:31], v[32:33] op_sel_hi:[1,0]
	v_pk_mul_f32 v[26:27], v[30:31], v[26:27]
	v_exp_f32_e32 v28, v28
	v_exp_f32_e32 v29, v29
	v_pk_mul_f32 v[26:27], v[26:27], v[34:35] op_sel_hi:[1,0]
	v_pk_mul_f32 v[16:17], v[20:21], v[16:17]
	v_exp_f32_e32 v36, v36
	v_pk_add_f32 v[28:29], v[28:29], 1.0 op_sel_hi:[1,0]
	v_exp_f32_e32 v37, v37
	v_rcp_f32_e32 v28, v28
	v_rcp_f32_e32 v29, v29
	v_pk_mul_f32 v[18:19], v[22:23], v[18:19]
	v_pk_add_f32 v[36:37], v[36:37], 1.0 op_sel_hi:[1,0]
	v_pk_mul_f32 v[24:25], v[24:25], v[34:35] op_sel_hi:[1,0]
	v_pk_mul_f32 v[26:27], v[26:27], v[28:29]
	v_pk_mul_f32 v[28:29], v[20:21], v[32:33] op_sel_hi:[1,0]
	v_pk_mul_f32 v[20:21], v[22:23], v[32:33] op_sel_hi:[1,0]
	v_exp_f32_e32 v28, v28
	v_exp_f32_e32 v29, v29
	v_exp_f32_e32 v20, v20
	v_exp_f32_e32 v21, v21
	v_rcp_f32_e32 v36, v36
	v_pk_add_f32 v[28:29], v[28:29], 1.0 op_sel_hi:[1,0]
	v_rcp_f32_e32 v37, v37
	v_pk_add_f32 v[20:21], v[20:21], 1.0 op_sel_hi:[1,0]
	v_rcp_f32_e32 v28, v28
	v_rcp_f32_e32 v29, v29
	v_rcp_f32_e32 v20, v20
	v_rcp_f32_e32 v21, v21
	v_pk_mul_f32 v[16:17], v[16:17], v[34:35] op_sel_hi:[1,0]
	v_pk_mul_f32 v[18:19], v[18:19], v[34:35] op_sel_hi:[1,0]
	v_pk_mul_f32 v[24:25], v[24:25], v[36:37]
	v_pk_mul_f32 v[16:17], v[16:17], v[28:29]
	v_pk_mul_f32 v[18:19], v[18:19], v[20:21]
	v_mov_b32_e32 v20, 0
	v_mov_b32_e32 v21, 0
	v_cvt_pk_fp8_f32 v20, v24, v25
	v_cvt_pk_fp8_f32 v21, v16, v17
	v_add_u32_e32 v16, 0xa0, v148
	v_mad_i64_i32 v[16:17], s[14:15], v16, s18, v[112:113]
	v_cvt_pk_fp8_f32 v20, v26, v27 op_sel:[0,0,1]
	v_cvt_pk_fp8_f32 v21, v18, v19 op_sel:[0,0,1]
	v_lshl_add_u64 v[16:17], v[16:17], 0, v[134:135]
	v_pk_mul_f32 v[8:9], v[12:13], v[8:9]
	v_mul_f32_e32 v18, v137, v137
	global_store_dwordx2 v[16:17], v[20:21], off
	v_mul_f32_e32 v16, 0xbfb8aa3b, v137
	v_pk_mul_f32 v[20:21], v[12:13], v[16:17] op_sel_hi:[1,0]
	v_pk_mul_f32 v[12:13], v[14:15], v[16:17] op_sel_hi:[1,0]
	v_pk_mul_f32 v[10:11], v[14:15], v[10:11]
	v_exp_f32_e32 v12, v12
	v_exp_f32_e32 v13, v13
	v_pk_mul_f32 v[10:11], v[10:11], v[18:19] op_sel_hi:[1,0]
	v_pk_mul_f32 v[0:1], v[4:5], v[0:1]
	v_exp_f32_e32 v20, v20
	v_pk_add_f32 v[12:13], v[12:13], 1.0 op_sel_hi:[1,0]
	v_exp_f32_e32 v21, v21
	v_rcp_f32_e32 v12, v12
	v_rcp_f32_e32 v13, v13
	v_pk_mul_f32 v[2:3], v[6:7], v[2:3]
	v_pk_add_f32 v[20:21], v[20:21], 1.0 op_sel_hi:[1,0]
	v_pk_mul_f32 v[8:9], v[8:9], v[18:19] op_sel_hi:[1,0]
	v_pk_mul_f32 v[10:11], v[10:11], v[12:13]
	v_pk_mul_f32 v[12:13], v[4:5], v[16:17] op_sel_hi:[1,0]
	v_pk_mul_f32 v[4:5], v[6:7], v[16:17] op_sel_hi:[1,0]
	v_exp_f32_e32 v12, v12
	v_exp_f32_e32 v13, v13
	v_exp_f32_e32 v4, v4
	v_exp_f32_e32 v5, v5
	v_rcp_f32_e32 v20, v20
	v_pk_add_f32 v[12:13], v[12:13], 1.0 op_sel_hi:[1,0]
	v_rcp_f32_e32 v21, v21
	v_pk_add_f32 v[4:5], v[4:5], 1.0 op_sel_hi:[1,0]
	v_rcp_f32_e32 v12, v12
	v_rcp_f32_e32 v13, v13
	v_rcp_f32_e32 v4, v4
	v_rcp_f32_e32 v5, v5
	v_pk_mul_f32 v[0:1], v[0:1], v[18:19] op_sel_hi:[1,0]
	v_pk_mul_f32 v[2:3], v[2:3], v[18:19] op_sel_hi:[1,0]
	v_pk_mul_f32 v[8:9], v[8:9], v[20:21]
	v_pk_mul_f32 v[0:1], v[0:1], v[12:13]
	v_pk_mul_f32 v[2:3], v[2:3], v[4:5]
	v_mov_b32_e32 v4, 0
	v_mov_b32_e32 v5, 0
	v_cvt_pk_fp8_f32 v4, v8, v9
	v_cvt_pk_fp8_f32 v5, v0, v1
	v_add_u32_e32 v0, 0xb0, v148
	v_mad_i64_i32 v[0:1], s[14:15], v0, s18, v[112:113]
	v_cvt_pk_fp8_f32 v4, v10, v11 op_sel:[0,0,1]
	v_cvt_pk_fp8_f32 v5, v2, v3 op_sel:[0,0,1]
	v_lshl_add_u64 v[0:1], v[0:1], 0, v[134:135]
	s_mov_b64 s[14:15], -1
	s_andn2_b64 vcc, exec, s[38:39]
	global_store_dwordx2 v[0:1], v[4:5], off
	s_cbranch_vccnz .LBB0_477
	s_lshl_b32 s14, s40, 8
	s_ashr_i32 s15, s14, 31
	v_lshl_add_u64 v[0:1], s[14:15], 2, v[132:133]
	global_load_dword v134, v[0:1], off
	s_andn2_b64 vcc, exec, s[8:9]
	s_cbranch_vccnz .LBB0_476
	s_mov_b32 s98, 1
	s_branch .LBB0_476
